# rtab row-statistics finish: lane^1 exchange via DPP quad_perm instead of ds_bpermute (5 sites)
# baseline (speedup 1.0000x reference)
; #define PG8_RTAB_LOAD(var, unit) do { if constexpr (Epi::NEEDS_R) { var = *(const uint4*)(E.ssq + (size_t)((unit).pm * BM + (tid >> 1)) * 16 + (tid & 1) * 8); } } while (0)
; #define PG8_RTAB_FIN(var, buf) do { if constexpr (Epi::NEEDS_R) { float ss_ = bflo(var.x) + bfhi(var.x) + bflo(var.y) + bfhi(var.y) + bflo(var.z) + bfhi(var.z) + bflo(var.w) + bfhi(var.w); ss_ += __shfl_xor(ss_, 1); \
;     if (!(tid & 1)) ((PG8_LAS float*)(lds + RT_OFF))[(buf) * 256 + (tid >> 1)] = rsqrtf(ss_ * (1.0f / DM) + EPS); } } while (0)
; template <class Epi>
; DI void gemm_phase(const bf16_t* __restrict__ gA, const bf16_t* __restrict__ gBt, int M, int N, int K, const Epi& E, char* lds_generic) {
;     ...
;   { uint4 rt0_ = {0u, 0u, 0u, 0u}; PG8_RTAB_LOAD(rt0_, cur); PG8_RTAB_FIN(rt0_, 0); }
.LBB0_124:
	s_andn2_b64 vcc, exec, s[84:85]
	s_cbranch_vccnz .LBB0_586
	v_readlane_b32 s4, v255, 52
	v_readlane_b32 s5, v255, 53
	s_mov_b64 s[0:1], -1
	s_and_b64 vcc, exec, s[4:5]
	s_cbranch_vccz .LBB0_147
	v_readlane_b32 s0, v253, 35
	v_mov_b32_e32 v2, v222
	v_readlane_b32 s1, v253, 36
	s_andn2_b64 vcc, exec, s[0:1]
	v_readfirstlane_b32 s4, v2
	s_cbranch_vccnz .LBB0_146
	v_ashrrev_i32_e32 v150, 1, v2
	v_readlane_b32 s0, v254, 49
	v_and_b32_e32 v3, 1, v2
	v_lshlrev_b32_e32 v0, 4, v3
	v_add_u32_e32 v4, s0, v150
	v_ashrrev_i32_e32 v5, 31, v4
	v_lshlrev_b64 v[4:5], 5, v[4:5]
	v_lshl_add_u64 v[4:5], s[70:71], 0, v[4:5]
	v_lshl_add_u64 v[4:5], v[4:5], 0, v[0:1]
	global_load_dwordx4 v[4:7], v[4:5], off
	v_cmp_lt_i32_e32 vcc, v224, v225
	v_cmp_eq_u32_e64 s[36:37], 0, v3
	v_lshl_add_u32 v152, v150, 2, v252
	s_waitcnt vmcnt(0)
	v_lshlrev_b32_e32 v0, 16, v4
	v_and_b32_e32 v4, 0xffff0000, v4
	v_add_f32_e32 v0, v0, v4
	v_lshlrev_b32_e32 v4, 16, v5
	v_add_f32_e32 v0, v0, v4
	v_and_b32_e32 v4, 0xffff0000, v5
	v_add_f32_e32 v0, v0, v4
	v_lshlrev_b32_e32 v4, 16, v6
	v_add_f32_e32 v0, v0, v4
	v_and_b32_e32 v4, 0xffff0000, v6
	v_add_f32_e32 v0, v0, v4
	v_lshlrev_b32_e32 v4, 16, v7
	v_add_f32_e32 v0, v0, v4
	v_and_b32_e32 v4, 0xffff0000, v7
	v_add_f32_e32 v0, v0, v4
	v_cndmask_b32_e32 v4, v223, v224, vcc
	v_lshlrev_b32_e32 v151, 2, v4
	s_nop 1
	v_mov_b32_dpp v4, v0 quad_perm:[1,0,3,2] row_mask:0xf bank_mask:0xf
	s_and_saveexec_b64 s[0:1], s[36:37]
	s_cbranch_execz .LBB0_129
	s_waitcnt lgkmcnt(0)
	v_add_f32_e32 v0, v0, v4
	v_fmamk_f32 v0, v0, 0x3a800000, v234
	v_mul_f32_e32 v4, 0x4b800000, v0
	v_cmp_gt_f32_e32 vcc, s97, v0
	s_nop 1
	v_cndmask_b32_e32 v0, v0, v4, vcc
	v_rsq_f32_e32 v0, v0
	s_nop 0
	v_mul_f32_e32 v4, 0x45800000, v0
	v_cndmask_b32_e32 v0, v0, v4, vcc
	ds_write_b32 v152, v0

; DI unsigned pack2(float lo, float hi) { f32x2_t v = {lo, hi}; return __builtin_bit_cast(unsigned, __builtin_convertvector(v, bf16x2_t)); }
; #define PG8_LAS __attribute__((address_space(3)))
;   DI void operator()(const f32x4 (&acc)[2][2][4][2], const Unit& u, int wr, int wc, int fr, int fq, const PG8_LAS float* rt) const {
;     const int row0 = u.pm * BM + wr * 64 + fr, col0 = u.pn * BM + wc * 32 + 8 * fq;
; #pragma unroll
;     for (int ai = 0; ai < 2; ++ai)
; #pragma unroll
;       for (int m = 0; m < 4; ++m) { bf16_t* rowp = O + (size_t)(row0 + ai * HALF + m * 16) * ldc + col0; const float r = rt[ai * HALF + wr * 64 + m * 16 + fr];
; #pragma unroll
;         for (int bj = 0; bj < 2; ++bj) { const f32x4 v0 = acc[ai][bj][m][0] * r, v1 = acc[ai][bj][m][1] * r;
;           u32x4 w; w.x = pack2(v0[0], v0[1]); w.y = pack2(v0[2], v0[3]); w.z = pack2(v1[0], v1[1]); w.w = pack2(v1[2], v1[3]);
;           *(u32x4*)(rowp + bj * HALF) = w; } }
;   }
.LBB0_140:
	s_lshl_b32 s1, s53, 10
	s_and_b32 s1, s1, 0x400
	v_add_u32_e32 v182, s1, v155
	ds_read2_b32 v[176:177], v182 offset1:16
	v_lshl_or_b32 v148, s58, 8, v156
	v_lshl_add_u32 v175, s59, 8, v153
	v_ashrrev_i32_e32 v149, 31, v148
	v_mov_b64_e32 v[146:147], s[66:67]
	s_movk_i32 s1, 0xc00
	v_mad_i64_i32 v[178:179], s[22:23], v175, s1, v[146:147]
	v_lshlrev_b64 v[148:149], 1, v[148:149]
	s_waitcnt lgkmcnt(0)
	v_pk_mul_f32 v[128:129], v[128:129], v[176:177] op_sel_hi:[1,0]
	v_pk_mul_f32 v[126:127], v[126:127], v[176:177] op_sel_hi:[1,0]
	v_pk_mul_f32 v[180:181], v[124:125], v[176:177] op_sel_hi:[1,0]
	v_pk_mul_f32 v[124:125], v[122:123], v[176:177] op_sel_hi:[1,0]
	v_lshl_add_u64 v[178:179], v[178:179], 0, v[148:149]
	v_cvt_pk_bf16_f32 v122, v126, v127
	v_cvt_pk_bf16_f32 v123, v128, v129
	v_cvt_pk_bf16_f32 v124, v124, v125
	v_cvt_pk_bf16_f32 v125, v180, v181
	global_store_dwordx4 v[178:179], v[122:125], off
	v_pk_mul_f32 v[116:117], v[116:117], v[176:177] op_sel_hi:[1,0]
	v_pk_mul_f32 v[114:115], v[114:115], v[176:177] op_sel_hi:[1,0]
	v_pk_mul_f32 v[122:123], v[108:109], v[176:177] op_sel_hi:[1,0]
	v_pk_mul_f32 v[108:109], v[106:107], v[176:177] op_sel_hi:[1,0]
	v_cvt_pk_bf16_f32 v106, v114, v115
	v_cvt_pk_bf16_f32 v107, v116, v117
	v_cvt_pk_bf16_f32 v108, v108, v109
	v_cvt_pk_bf16_f32 v109, v122, v123
	global_store_dwordx4 v[178:179], v[106:109], off offset:256
	v_mov_b32_e32 v116, v177
	v_pk_mul_f32 v[112:113], v[112:113], v[116:117] op_sel_hi:[1,0]
	v_or_b32_e32 v106, 16, v175
	v_mad_i64_i32 v[106:107], s[22:23], v106, s1, v[146:147]
	v_lshl_add_u64 v[114:115], v[106:107], 0, v[148:149]
	v_pk_mul_f32 v[108:109], v[120:121], v[116:117] op_sel_hi:[1,0]
	v_pk_mul_f32 v[106:107], v[118:119], v[116:117] op_sel_hi:[1,0]
	v_pk_mul_f32 v[110:111], v[110:111], v[116:117] op_sel_hi:[1,0]
	v_cvt_pk_bf16_f32 v106, v106, v107
	v_cvt_pk_bf16_f32 v107, v108, v109
	v_cvt_pk_bf16_f32 v108, v110, v111
	v_cvt_pk_bf16_f32 v109, v112, v113
	global_store_dwordx4 v[114:115], v[106:109], off
	v_pk_mul_f32 v[104:105], v[104:105], v[116:117] op_sel_hi:[1,0]
	v_pk_mul_f32 v[102:103], v[102:103], v[116:117] op_sel_hi:[1,0]
	v_pk_mul_f32 v[106:107], v[96:97], v[116:117] op_sel_hi:[1,0]
	v_pk_mul_f32 v[96:97], v[94:95], v[116:117] op_sel_hi:[1,0]
	v_cvt_pk_bf16_f32 v94, v102, v103
	v_cvt_pk_bf16_f32 v95, v104, v105
	v_cvt_pk_bf16_f32 v96, v96, v97
	v_cvt_pk_bf16_f32 v97, v106, v107
	global_store_dwordx4 v[114:115], v[94:97], off offset:256
	ds_read2_b32 v[94:95], v182 offset0:32 offset1:48
	s_andn2_b64 vcc, exec, s[38:39]
	v_or_b32_e32 v96, 32, v175
	v_mad_i64_i32 v[96:97], s[22:23], v96, s1, v[146:147]
	s_waitcnt lgkmcnt(0)
	v_pk_mul_f32 v[100:101], v[100:101], v[94:95] op_sel_hi:[1,0]
	v_pk_mul_f32 v[98:99], v[98:99], v[94:95] op_sel_hi:[1,0]
	v_pk_mul_f32 v[102:103], v[92:93], v[94:95] op_sel_hi:[1,0]
	v_pk_mul_f32 v[92:93], v[90:91], v[94:95] op_sel_hi:[1,0]
	v_lshl_add_u64 v[96:97], v[96:97], 0, v[148:149]
	v_cvt_pk_bf16_f32 v90, v98, v99
	v_cvt_pk_bf16_f32 v91, v100, v101
	v_cvt_pk_bf16_f32 v92, v92, v93
	v_cvt_pk_bf16_f32 v93, v102, v103
	global_store_dwordx4 v[96:97], v[90:93], off
	v_pk_mul_f32 v[84:85], v[84:85], v[94:95] op_sel_hi:[1,0]
	v_pk_mul_f32 v[82:83], v[82:83], v[94:95] op_sel_hi:[1,0]
	v_pk_mul_f32 v[90:91], v[76:77], v[94:95] op_sel_hi:[1,0]
	v_pk_mul_f32 v[76:77], v[74:75], v[94:95] op_sel_hi:[1,0]
	v_cvt_pk_bf16_f32 v74, v82, v83
	v_cvt_pk_bf16_f32 v75, v84, v85
	v_cvt_pk_bf16_f32 v76, v76, v77
	v_cvt_pk_bf16_f32 v77, v90, v91
	global_store_dwordx4 v[96:97], v[74:77], off offset:256
	v_mov_b32_e32 v84, v95
	v_pk_mul_f32 v[80:81], v[80:81], v[84:85] op_sel_hi:[1,0]
	v_or_b32_e32 v74, 48, v175
	v_mad_i64_i32 v[74:75], s[22:23], v74, s1, v[146:147]
	v_lshl_add_u64 v[82:83], v[74:75], 0, v[148:149]
	v_pk_mul_f32 v[76:77], v[88:89], v[84:85] op_sel_hi:[1,0]
	v_pk_mul_f32 v[74:75], v[86:87], v[84:85] op_sel_hi:[1,0]
	v_pk_mul_f32 v[78:79], v[78:79], v[84:85] op_sel_hi:[1,0]
	v_cvt_pk_bf16_f32 v74, v74, v75
	v_cvt_pk_bf16_f32 v75, v76, v77
	v_cvt_pk_bf16_f32 v76, v78, v79
	v_cvt_pk_bf16_f32 v77, v80, v81
	global_store_dwordx4 v[82:83], v[74:77], off
	v_pk_mul_f32 v[72:73], v[72:73], v[84:85] op_sel_hi:[1,0]
	v_pk_mul_f32 v[70:71], v[70:71], v[84:85] op_sel_hi:[1,0]
	v_pk_mul_f32 v[74:75], v[68:69], v[84:85] op_sel_hi:[1,0]
	v_pk_mul_f32 v[68:69], v[66:67], v[84:85] op_sel_hi:[1,0]
	v_cvt_pk_bf16_f32 v66, v70, v71
	v_cvt_pk_bf16_f32 v67, v72, v73
	v_cvt_pk_bf16_f32 v68, v68, v69
	v_cvt_pk_bf16_f32 v69, v74, v75
	global_store_dwordx4 v[82:83], v[66:69], off offset:256
	ds_read2_b32 v[66:67], v182 offset0:128 offset1:144
	s_mov_b64 s[28:29], -1
	v_add_u32_e32 v68, 0x80, v175
	v_mad_i64_i32 v[68:69], s[22:23], v68, s1, v[146:147]
	s_waitcnt lgkmcnt(0)
; DI unsigned pack2(float lo, float hi) { f32x2_t v = {lo, hi}; return __builtin_bit_cast(unsigned, __builtin_convertvector(v, bf16x2_t)); }
;   DI void operator()(const f32x4 (&acc)[2][2][4][2], const Unit& u, int wr, int wc, int fr, int fq, const PG8_LAS float* rt) const {
;     ...
;     for (int ai = 0; ai < 2; ++ai)
; #pragma unroll
;       for (int m = 0; m < 4; ++m) { bf16_t* rowp = O + (size_t)(row0 + ai * HALF + m * 16) * ldc + col0; const float r = rt[ai * HALF + wr * 64 + m * 16 + fr];
; #pragma unroll
;         for (int bj = 0; bj < 2; ++bj) { const f32x4 v0 = acc[ai][bj][m][0] * r, v1 = acc[ai][bj][m][1] * r;
;           u32x4 w; w.x = pack2(v0[0], v0[1]); w.y = pack2(v0[2], v0[3]); w.z = pack2(v1[0], v1[1]); w.w = pack2(v1[2], v1[3]);
;           *(u32x4*)(rowp + bj * HALF) = w; } }
	v_pk_mul_f32 v[64:65], v[64:65], v[66:67] op_sel_hi:[1,0]
	v_pk_mul_f32 v[62:63], v[62:63], v[66:67] op_sel_hi:[1,0]
	v_pk_mul_f32 v[70:71], v[60:61], v[66:67] op_sel_hi:[1,0]
	v_pk_mul_f32 v[60:61], v[58:59], v[66:67] op_sel_hi:[1,0]
	v_lshl_add_u64 v[68:69], v[68:69], 0, v[148:149]
	v_cvt_pk_bf16_f32 v58, v62, v63
	v_cvt_pk_bf16_f32 v59, v64, v65
	v_cvt_pk_bf16_f32 v60, v60, v61
	v_cvt_pk_bf16_f32 v61, v70, v71
	global_store_dwordx4 v[68:69], v[58:61], off
	v_pk_mul_f32 v[52:53], v[52:53], v[66:67] op_sel_hi:[1,0]
	v_pk_mul_f32 v[50:51], v[50:51], v[66:67] op_sel_hi:[1,0]
	v_pk_mul_f32 v[58:59], v[44:45], v[66:67] op_sel_hi:[1,0]
	v_pk_mul_f32 v[44:45], v[42:43], v[66:67] op_sel_hi:[1,0]
	v_cvt_pk_bf16_f32 v42, v50, v51
	v_cvt_pk_bf16_f32 v43, v52, v53
	v_cvt_pk_bf16_f32 v44, v44, v45
	v_cvt_pk_bf16_f32 v45, v58, v59
	global_store_dwordx4 v[68:69], v[42:45], off offset:256
	v_mov_b32_e32 v52, v67
	v_pk_mul_f32 v[48:49], v[48:49], v[52:53] op_sel_hi:[1,0]
	v_add_u32_e32 v42, 0x90, v175
	v_mad_i64_i32 v[42:43], s[22:23], v42, s1, v[146:147]
	v_lshl_add_u64 v[50:51], v[42:43], 0, v[148:149]
	v_pk_mul_f32 v[44:45], v[56:57], v[52:53] op_sel_hi:[1,0]
	v_pk_mul_f32 v[42:43], v[54:55], v[52:53] op_sel_hi:[1,0]
	v_pk_mul_f32 v[46:47], v[46:47], v[52:53] op_sel_hi:[1,0]
	v_cvt_pk_bf16_f32 v42, v42, v43
	v_cvt_pk_bf16_f32 v43, v44, v45
	v_cvt_pk_bf16_f32 v44, v46, v47
	v_cvt_pk_bf16_f32 v45, v48, v49
	global_store_dwordx4 v[50:51], v[42:45], off
	v_pk_mul_f32 v[40:41], v[40:41], v[52:53] op_sel_hi:[1,0]
	v_pk_mul_f32 v[38:39], v[38:39], v[52:53] op_sel_hi:[1,0]
	v_pk_mul_f32 v[42:43], v[32:33], v[52:53] op_sel_hi:[1,0]
	v_pk_mul_f32 v[32:33], v[30:31], v[52:53] op_sel_hi:[1,0]
	v_cvt_pk_bf16_f32 v30, v38, v39
	v_cvt_pk_bf16_f32 v31, v40, v41
	v_cvt_pk_bf16_f32 v32, v32, v33
	v_cvt_pk_bf16_f32 v33, v42, v43
	global_store_dwordx4 v[50:51], v[30:33], off offset:256
	ds_read2_b32 v[30:31], v182 offset0:160 offset1:176
	s_waitcnt lgkmcnt(0)
	v_pk_mul_f32 v[36:37], v[36:37], v[30:31] op_sel_hi:[1,0]
	v_add_u32_e32 v32, 0xa0, v175
	v_mad_i64_i32 v[32:33], s[22:23], v32, s1, v[146:147]
	v_pk_mul_f32 v[34:35], v[34:35], v[30:31] op_sel_hi:[1,0]
	v_pk_mul_f32 v[38:39], v[28:29], v[30:31] op_sel_hi:[1,0]
	v_pk_mul_f32 v[28:29], v[26:27], v[30:31] op_sel_hi:[1,0]
	v_lshl_add_u64 v[32:33], v[32:33], 0, v[148:149]
	v_cvt_pk_bf16_f32 v26, v34, v35
	v_cvt_pk_bf16_f32 v27, v36, v37
	v_cvt_pk_bf16_f32 v28, v28, v29
	v_cvt_pk_bf16_f32 v29, v38, v39
	global_store_dwordx4 v[32:33], v[26:29], off
	v_pk_mul_f32 v[20:21], v[20:21], v[30:31] op_sel_hi:[1,0]
	v_pk_mul_f32 v[18:19], v[18:19], v[30:31] op_sel_hi:[1,0]
	v_pk_mul_f32 v[26:27], v[12:13], v[30:31] op_sel_hi:[1,0]
	v_pk_mul_f32 v[12:13], v[10:11], v[30:31] op_sel_hi:[1,0]
	v_cvt_pk_bf16_f32 v10, v18, v19
	v_cvt_pk_bf16_f32 v11, v20, v21
	v_cvt_pk_bf16_f32 v12, v12, v13
	v_cvt_pk_bf16_f32 v13, v26, v27
	global_store_dwordx4 v[32:33], v[10:13], off offset:256
	v_mov_b32_e32 v20, v31
	v_pk_mul_f32 v[16:17], v[16:17], v[20:21] op_sel_hi:[1,0]
	v_add_u32_e32 v10, 0xb0, v175
	v_mad_i64_i32 v[10:11], s[22:23], v10, s1, v[146:147]
	v_lshl_add_u64 v[18:19], v[10:11], 0, v[148:149]
	v_pk_mul_f32 v[12:13], v[24:25], v[20:21] op_sel_hi:[1,0]
	v_pk_mul_f32 v[10:11], v[22:23], v[20:21] op_sel_hi:[1,0]
	v_pk_mul_f32 v[14:15], v[14:15], v[20:21] op_sel_hi:[1,0]
	v_cvt_pk_bf16_f32 v10, v10, v11
	v_cvt_pk_bf16_f32 v11, v12, v13
	v_cvt_pk_bf16_f32 v12, v14, v15
	v_cvt_pk_bf16_f32 v13, v16, v17
	global_store_dwordx4 v[18:19], v[10:13], off
	v_pk_mul_f32 v[8:9], v[8:9], v[20:21] op_sel_hi:[1,0]
	v_pk_mul_f32 v[6:7], v[6:7], v[20:21] op_sel_hi:[1,0]
	v_pk_mul_f32 v[10:11], v[4:5], v[20:21] op_sel_hi:[1,0]
	v_pk_mul_f32 v[4:5], v[2:3], v[20:21] op_sel_hi:[1,0]
	v_cvt_pk_bf16_f32 v2, v6, v7
	v_cvt_pk_bf16_f32 v3, v8, v9
	v_cvt_pk_bf16_f32 v4, v4, v5
	v_cvt_pk_bf16_f32 v5, v10, v11
	global_store_dwordx4 v[18:19], v[2:5], off offset:256
	s_cbranch_vccnz .LBB0_133
	s_waitcnt vmcnt(16)
	v_lshlrev_b32_e32 v2, 16, v130
	v_and_b32_e32 v3, 0xffff0000, v130
	v_add_f32_e32 v2, v2, v3
	v_lshlrev_b32_e32 v3, 16, v131
	v_add_f32_e32 v2, v2, v3
	v_and_b32_e32 v3, 0xffff0000, v131
	v_add_f32_e32 v2, v2, v3
	v_lshlrev_b32_e32 v3, 16, v132
	v_add_f32_e32 v2, v2, v3
	v_and_b32_e32 v3, 0xffff0000, v132
	v_add_f32_e32 v2, v2, v3
	v_lshlrev_b32_e32 v3, 16, v133
	v_add_f32_e32 v2, v2, v3
	v_and_b32_e32 v3, 0xffff0000, v133
	v_add_f32_e32 v2, v2, v3
	s_nop 1
	v_mov_b32_dpp v3, v2 quad_perm:[1,0,3,2] row_mask:0xf bank_mask:0xf
	s_and_saveexec_b64 s[22:23], s[36:37]
	s_xor_b64 s[28:29], exec, s[22:23]
	s_cbranch_execz .LBB0_132
	s_waitcnt lgkmcnt(0)
	v_add_f32_e32 v2, v2, v3
	v_fmamk_f32 v2, v2, 0x3a800000, v234
	v_cmp_gt_f32_e32 vcc, s97, v2
	v_mul_f32_e32 v3, 0x4b800000, v2
	s_lshl_b32 s1, s42, 10
	v_cndmask_b32_e32 v2, v2, v3, vcc
	v_rsq_f32_e32 v2, v2
	s_and_b32 s1, s1, 0x400
	v_mul_f32_e32 v3, 0x45800000, v2
	v_cndmask_b32_e32 v2, v2, v3, vcc
	v_add_u32_e32 v3, s1, v152
	ds_write_b32 v3, v2
	s_branch .LBB0_132

; #define PG8_RTAB_LOAD(var, unit) do { if constexpr (Epi::NEEDS_R) { var = *(const uint4*)(E.ssq + (size_t)((unit).pm * BM + (tid >> 1)) * 16 + (tid & 1) * 8); } } while (0)
; #define PG8_RTAB_FIN(var, buf) do { if constexpr (Epi::NEEDS_R) { float ss_ = bflo(var.x) + bfhi(var.x) + bflo(var.y) + bfhi(var.y) + bflo(var.z) + bfhi(var.z) + bflo(var.w) + bfhi(var.w); ss_ += __shfl_xor(ss_, 1); \
;     if (!(tid & 1)) ((PG8_LAS float*)(lds + RT_OFF))[(buf) * 256 + (tid >> 1)] = rsqrtf(ss_ * (1.0f / DM) + EPS); } } while (0)
; template <class Epi>
; DI void gemm_phase(const bf16_t* __restrict__ gA, const bf16_t* __restrict__ gBt, int M, int N, int K, const Epi& E, char* lds_generic) {
;     ...
;   { uint4 rt0_ = {0u, 0u, 0u, 0u}; PG8_RTAB_LOAD(rt0_, cur); PG8_RTAB_FIN(rt0_, 0); }
.LBB0_147:
	s_andn2_b64 vcc, exec, s[0:1]
	s_cbranch_vccnz .LBB0_168
	v_readlane_b32 s0, v253, 37
	v_mov_b32_e32 v2, v222
	v_readlane_b32 s1, v253, 38
	s_andn2_b64 vcc, exec, s[0:1]
	v_readfirstlane_b32 s4, v2
	s_cbranch_vccnz .LBB0_168
	v_ashrrev_i32_e32 v150, 1, v2
	v_readlane_b32 s0, v254, 62
	v_and_b32_e32 v6, 1, v2
	v_lshlrev_b32_e32 v0, 4, v6
	v_add_u32_e32 v4, s0, v150
	v_ashrrev_i32_e32 v5, 31, v4
	v_lshlrev_b64 v[4:5], 5, v[4:5]
	v_lshl_add_u64 v[4:5], s[70:71], 0, v[4:5]
	v_lshl_add_u64 v[4:5], v[4:5], 0, v[0:1]
	global_load_dwordx4 v[8:11], v[4:5], off
	v_cmp_lt_i32_e32 vcc, v224, v225
	v_cmp_eq_u32_e64 s[36:37], 0, v6
	v_lshl_add_u32 v152, v150, 2, v252
	s_waitcnt vmcnt(0)
	v_lshlrev_b32_e32 v0, 16, v8
	s_waitcnt lgkmcnt(0)
	v_and_b32_e32 v3, 0xffff0000, v8
	v_add_f32_e32 v0, v0, v3
	v_lshlrev_b32_e32 v3, 16, v9
	v_add_f32_e32 v0, v0, v3
	v_and_b32_e32 v3, 0xffff0000, v9
	v_add_f32_e32 v0, v0, v3
	v_lshlrev_b32_e32 v3, 16, v10
	v_add_f32_e32 v0, v0, v3
	v_and_b32_e32 v3, 0xffff0000, v10
	v_add_f32_e32 v0, v0, v3
	v_lshlrev_b32_e32 v3, 16, v11
	v_add_f32_e32 v0, v0, v3
	v_and_b32_e32 v3, 0xffff0000, v11
	v_add_f32_e32 v0, v0, v3
	v_cndmask_b32_e32 v3, v223, v224, vcc
	v_lshlrev_b32_e32 v151, 2, v3
	s_nop 1
	v_mov_b32_dpp v3, v0 quad_perm:[1,0,3,2] row_mask:0xf bank_mask:0xf
	s_and_saveexec_b64 s[0:1], s[36:37]
	s_cbranch_execz .LBB0_151
	s_waitcnt lgkmcnt(0)
	v_add_f32_e32 v0, v0, v3
	v_fmamk_f32 v0, v0, 0x3a800000, v234
	v_mul_f32_e32 v3, 0x4b800000, v0
	v_cmp_gt_f32_e32 vcc, s97, v0
	s_nop 1
	v_cndmask_b32_e32 v0, v0, v3, vcc
	v_rsq_f32_e32 v0, v0
	s_nop 0
	v_mul_f32_e32 v3, 0x45800000, v0
	v_cndmask_b32_e32 v0, v0, v3, vcc
	ds_write_b32 v152, v0

; #define PG8_RTAB_LOAD(var, unit) do { if constexpr (Epi::NEEDS_R) { var = *(const uint4*)(E.ssq + (size_t)((unit).pm * BM + (tid >> 1)) * 16 + (tid & 1) * 8); } } while (0)
; #define PG8_RTAB_FIN(var, buf) do { if constexpr (Epi::NEEDS_R) { float ss_ = bflo(var.x) + bfhi(var.x) + bflo(var.y) + bfhi(var.y) + bflo(var.z) + bfhi(var.z) + bflo(var.w) + bfhi(var.w); ss_ += __shfl_xor(ss_, 1); \
;     if (!(tid & 1)) ((PG8_LAS float*)(lds + RT_OFF))[(buf) * 256 + (tid >> 1)] = rsqrtf(ss_ * (1.0f / DM) + EPS); } } while (0)
; template <class Epi>
; DI void gemm_phase(const bf16_t* __restrict__ gA, const bf16_t* __restrict__ gBt, int M, int N, int K, const Epi& E, char* lds_generic) {
;     ...
;   { uint4 rt0_ = {0u, 0u, 0u, 0u}; PG8_RTAB_LOAD(rt0_, cur); PG8_RTAB_FIN(rt0_, 0); }
; __global__ void __launch_bounds__(512) fwd_megakernel(Params p) {
;     ...
;         const size_t ro = (size_t)c * rows;
;         gemm_phase(p.h16 + ro * DM, p.wts + (f ? W_UPB : W_UPA), rows, 2 * DFF, DM, EpiUp{p.big, p.ssq + ro * 16}, lds);
.LBB0_590:
	v_readlane_b32 s0, v255, 19
	s_mul_hi_u32 s1, s33, s0
	s_mul_i32 s0, s33, s0
	s_lshl_b64 s[6:7], s[0:1], 11
	s_add_u32 s82, s92, s6
	s_addc_u32 s83, s93, s7
	s_lshl_b64 s[6:7], s[0:1], 5
	s_add_u32 s84, s70, s6
	s_addc_u32 s85, s71, s7
	v_readlane_b32 s6, v255, 13
	v_mov_b32_e32 v2, v222
	v_readlane_b32 s7, v255, 14
	s_andn2_b64 vcc, exec, s[6:7]
	v_readfirstlane_b32 s76, v2
	s_cbranch_vccnz .LBB0_614
	v_ashrrev_i32_e32 v150, 1, v2
	v_readlane_b32 s6, v255, 26
	v_cmp_lt_i32_e32 vcc, v224, v225
	v_lshl_add_u32 v152, v150, 2, v252
	v_add_u32_e32 v4, s6, v150
	v_ashrrev_i32_e32 v5, 31, v4
	v_lshlrev_b64 v[4:5], 5, v[4:5]
	v_lshl_add_u64 v[6:7], s[84:85], 0, v[4:5]
	v_and_b32_e32 v4, 1, v2
	v_lshlrev_b32_e32 v0, 4, v4
	v_lshl_add_u64 v[6:7], v[6:7], 0, v[0:1]
	global_load_dwordx4 v[6:9], v[6:7], off
	v_cmp_eq_u32_e64 s[36:37], 0, v4
	s_waitcnt vmcnt(0)
	v_lshlrev_b32_e32 v0, 16, v6
	v_and_b32_e32 v3, 0xffff0000, v6
	v_add_f32_e32 v0, v0, v3
	v_lshlrev_b32_e32 v3, 16, v7
	v_add_f32_e32 v0, v0, v3
	v_and_b32_e32 v3, 0xffff0000, v7
	v_add_f32_e32 v0, v0, v3
	v_lshlrev_b32_e32 v3, 16, v8
	v_add_f32_e32 v0, v0, v3
	v_and_b32_e32 v3, 0xffff0000, v8
	v_add_f32_e32 v0, v0, v3
	v_lshlrev_b32_e32 v3, 16, v9
	v_add_f32_e32 v0, v0, v3
	v_and_b32_e32 v3, 0xffff0000, v9
	v_add_f32_e32 v0, v0, v3
	v_cndmask_b32_e32 v3, v223, v224, vcc
	v_lshlrev_b32_e32 v151, 2, v3
	s_nop 1
	v_mov_b32_dpp v3, v0 quad_perm:[1,0,3,2] row_mask:0xf bank_mask:0xf
	s_and_saveexec_b64 s[26:27], s[36:37]
	s_cbranch_execz .LBB0_593
	s_waitcnt lgkmcnt(0)
	v_add_f32_e32 v0, v0, v3
	v_fmamk_f32 v0, v0, 0x3a800000, v234
	v_mul_f32_e32 v3, 0x4b800000, v0
	v_cmp_gt_f32_e32 vcc, s97, v0
	s_nop 1
	v_cndmask_b32_e32 v0, v0, v3, vcc
	v_rsq_f32_e32 v0, v0
	s_nop 0
	v_mul_f32_e32 v3, 0x45800000, v0
	v_cndmask_b32_e32 v0, v0, v3, vcc
	ds_write_b32 v152, v0

; DI unsigned pack2(float lo, float hi) { f32x2_t v = {lo, hi}; return __builtin_bit_cast(unsigned, __builtin_convertvector(v, bf16x2_t)); }
; #define PG8_LAS __attribute__((address_space(3)))
;   DI void operator()(const f32x4 (&acc)[2][2][4][2], const Unit& u, int wr, int wc, int fr, int fq, const PG8_LAS float* rt) const {
;     const int row0 = u.pm * BM + wr * 64 + fr, col0 = u.pn * HALF + wc * 32 + 8 * fq;
; #pragma unroll
;     for (int ai = 0; ai < 2; ++ai)
; #pragma unroll
;       for (int m = 0; m < 4; ++m) {
;         const float r = rt[ai * HALF + wr * 64 + m * 16 + fr];
;         float a[8];
; #pragma unroll
;         for (int n = 0; n < 2; ++n)
; #pragma unroll
;           for (int j = 0; j < 4; ++j) { const float u1 = acc[ai][0][m][n][j] * r, u3 = acc[ai][1][m][n][j] * r; a[4 * n + j] = u1 * u3 * __builtin_amdgcn_rcpf(1.f + __builtin_amdgcn_exp2f(-LOG2E * u1)); }
;         u32x4 w; w.x = pack2(a[0], a[1]); w.y = pack2(a[2], a[3]); w.z = pack2(a[4], a[5]); w.w = pack2(a[6], a[7]);
;         *(u32x4*)(O + (size_t)(row0 + ai * HALF + m * 16) * DFF + col0) = w; }
.LBB0_608:
	s_lshl_b32 s8, s8, 10
	s_and_b32 s8, s8, 0x400
	v_add_u32_e32 v159, s8, v156
	ds_read2_b32 v[148:149], v159 offset1:16
	v_lshl_or_b32 v146, s9, 7, v157
	v_lshl_add_u32 v158, s19, 8, v153
	v_ashrrev_i32_e32 v147, 31, v146
	s_mov_b64 s[28:29], -1
	s_waitcnt lgkmcnt(0)
	v_pk_mul_f32 v[130:131], v[130:131], v[148:149] op_sel_hi:[1,0]
	v_pk_mul_f32 v[126:127], v[126:127], v[148:149] op_sel_hi:[1,0]
	v_mul_f32_e32 v160, 0xbfb8aa3b, v130
	v_pk_mul_f32 v[126:127], v[130:131], v[126:127]
	v_mul_f32_e32 v130, 0xbfb8aa3b, v131
	v_exp_f32_e32 v130, v130
	v_pk_mul_f32 v[128:129], v[128:129], v[148:149] op_sel_hi:[1,0]
	v_pk_mul_f32 v[122:123], v[122:123], v[148:149] op_sel_hi:[1,0]
	v_pk_mul_f32 v[118:119], v[118:119], v[148:149] op_sel_hi:[1,0]
	v_add_f32_e32 v130, 1.0, v130
	v_rcp_f32_e32 v161, v130
	v_pk_mul_f32 v[130:131], v[132:133], v[148:149] op_sel_hi:[1,0]
	v_pk_mul_f32 v[118:119], v[122:123], v[118:119]
	v_mul_f32_e32 v132, 0xbfb8aa3b, v130
	v_pk_mul_f32 v[128:129], v[130:131], v[128:129]
	v_mul_f32_e32 v130, 0xbfb8aa3b, v131
	v_exp_f32_e32 v130, v130
	v_pk_mul_f32 v[120:121], v[120:121], v[148:149] op_sel_hi:[1,0]
	v_exp_f32_e32 v160, v160
	v_exp_f32_e32 v132, v132
	v_add_f32_e32 v130, 1.0, v130
	v_rcp_f32_e32 v133, v130
	v_mul_f32_e32 v130, 0xbfb8aa3b, v122
	v_mul_f32_e32 v122, 0xbfb8aa3b, v123
	v_exp_f32_e32 v122, v122
	v_exp_f32_e32 v130, v130
	v_add_f32_e32 v160, 1.0, v160
	v_rcp_f32_e32 v160, v160
	v_add_f32_e32 v122, 1.0, v122
	v_rcp_f32_e32 v131, v122
	v_pk_mul_f32 v[122:123], v[124:125], v[148:149] op_sel_hi:[1,0]
	v_add_f32_e32 v130, 1.0, v130
	v_mul_f32_e32 v124, 0xbfb8aa3b, v122
	v_pk_mul_f32 v[120:121], v[122:123], v[120:121]
	v_mul_f32_e32 v122, 0xbfb8aa3b, v123
	v_exp_f32_e32 v124, v124
	v_exp_f32_e32 v122, v122
	v_rcp_f32_e32 v130, v130
	v_add_f32_e32 v132, 1.0, v132
	v_add_f32_e32 v124, 1.0, v124
	v_add_f32_e32 v122, 1.0, v122
	v_rcp_f32_e32 v124, v124
	v_rcp_f32_e32 v125, v122
	v_rcp_f32_e32 v132, v132
	v_pk_mul_f32 v[118:119], v[118:119], v[130:131]
	v_pk_mul_f32 v[126:127], v[126:127], v[160:161]
	v_pk_mul_f32 v[120:121], v[120:121], v[124:125]
	v_cvt_pk_bf16_f32 v124, v118, v119
	v_mov_b64_e32 v[118:119], s[66:67]
	v_pk_mul_f32 v[128:129], v[128:129], v[132:133]
	v_cvt_pk_bf16_f32 v122, v126, v127
	v_cvt_pk_bf16_f32 v125, v120, v121
	v_mad_i64_i32 v[126:127], s[8:9], v158, s43, v[118:119]
	v_lshlrev_b64 v[120:121], 1, v[146:147]
	v_cvt_pk_bf16_f32 v123, v128, v129
	v_lshl_add_u64 v[126:127], v[126:127], 0, v[120:121]
	global_store_dwordx4 v[126:127], v[122:125], off
	s_andn2_b64 vcc, exec, s[38:39]
	s_nop 0
	v_mov_b32_e32 v122, v149
	v_pk_mul_f32 v[114:115], v[114:115], v[122:123] op_sel_hi:[1,0]
	s_nop 0
	v_mul_f32_e32 v123, 0xbfb8aa3b, v114
	v_exp_f32_e32 v123, v123
	s_nop 0
	v_add_f32_e32 v123, 1.0, v123
	v_pk_mul_f32 v[110:111], v[110:111], v[122:123] op_sel_hi:[1,0]
	v_pk_mul_f32 v[112:113], v[112:113], v[122:123] op_sel_hi:[1,0]
	v_pk_mul_f32 v[110:111], v[114:115], v[110:111]
	v_mul_f32_e32 v114, 0xbfb8aa3b, v115
	v_exp_f32_e32 v114, v114
	v_pk_mul_f32 v[106:107], v[106:107], v[122:123] op_sel_hi:[1,0]
	v_pk_mul_f32 v[102:103], v[102:103], v[122:123] op_sel_hi:[1,0]
	v_pk_mul_f32 v[104:105], v[104:105], v[122:123] op_sel_hi:[1,0]
	v_add_f32_e32 v114, 1.0, v114
	v_rcp_f32_e32 v125, v114
	v_pk_mul_f32 v[114:115], v[116:117], v[122:123] op_sel_hi:[1,0]
	v_pk_mul_f32 v[102:103], v[106:107], v[102:103]
	v_mul_f32_e32 v116, 0xbfb8aa3b, v114
	v_pk_mul_f32 v[112:113], v[114:115], v[112:113]
	v_mul_f32_e32 v114, 0xbfb8aa3b, v115
	v_exp_f32_e32 v114, v114
	v_exp_f32_e32 v116, v116
	v_rcp_f32_e32 v124, v123
	v_add_f32_e32 v114, 1.0, v114
	v_rcp_f32_e32 v117, v114
	v_mul_f32_e32 v114, 0xbfb8aa3b, v106
	v_mul_f32_e32 v106, 0xbfb8aa3b, v107
	v_exp_f32_e32 v114, v114
	v_exp_f32_e32 v106, v106
	v_add_f32_e32 v116, 1.0, v116
	v_rcp_f32_e32 v116, v116
	v_add_f32_e32 v114, 1.0, v114
	v_add_f32_e32 v106, 1.0, v106
	v_rcp_f32_e32 v114, v114
	v_rcp_f32_e32 v115, v106
	v_pk_mul_f32 v[110:111], v[110:111], v[124:125]
	v_pk_mul_f32 v[112:113], v[112:113], v[116:117]
	v_pk_mul_f32 v[106:107], v[102:103], v[114:115]
	v_pk_mul_f32 v[102:103], v[108:109], v[122:123] op_sel_hi:[1,0]
	s_nop 0
	v_mul_f32_e32 v108, 0xbfb8aa3b, v102
	v_pk_mul_f32 v[104:105], v[102:103], v[104:105]
	v_mul_f32_e32 v102, 0xbfb8aa3b, v103
	v_exp_f32_e32 v108, v108
	v_exp_f32_e32 v102, v102
	v_cvt_pk_bf16_f32 v103, v112, v113
	v_add_f32_e32 v108, 1.0, v108
	v_add_f32_e32 v102, 1.0, v102
	v_rcp_f32_e32 v108, v108
	v_rcp_f32_e32 v109, v102
	v_cvt_pk_bf16_f32 v102, v110, v111
	v_pk_mul_f32 v[108:109], v[104:105], v[108:109]
	v_cvt_pk_bf16_f32 v104, v106, v107
	v_or_b32_e32 v106, 16, v158
	v_mad_i64_i32 v[106:107], s[8:9], v106, s43, v[118:119]
	v_cvt_pk_bf16_f32 v105, v108, v109
	v_lshl_add_u64 v[106:107], v[106:107], 0, v[120:121]
	global_store_dwordx4 v[106:107], v[102:105], off
	ds_read2_b32 v[102:103], v159 offset0:32 offset1:48
	s_waitcnt lgkmcnt(0)
; DI unsigned pack2(float lo, float hi) { f32x2_t v = {lo, hi}; return __builtin_bit_cast(unsigned, __builtin_convertvector(v, bf16x2_t)); }
;   DI void operator()(const f32x4 (&acc)[2][2][4][2], const Unit& u, int wr, int wc, int fr, int fq, const PG8_LAS float* rt) const {
;     ...
;       for (int m = 0; m < 4; ++m) {
;         const float r = rt[ai * HALF + wr * 64 + m * 16 + fr];
;         float a[8];
; #pragma unroll
;         for (int n = 0; n < 2; ++n)
; #pragma unroll
;           for (int j = 0; j < 4; ++j) { const float u1 = acc[ai][0][m][n][j] * r, u3 = acc[ai][1][m][n][j] * r; a[4 * n + j] = u1 * u3 * __builtin_amdgcn_rcpf(1.f + __builtin_amdgcn_exp2f(-LOG2E * u1)); }
;         u32x4 w; w.x = pack2(a[0], a[1]); w.y = pack2(a[2], a[3]); w.z = pack2(a[4], a[5]); w.w = pack2(a[6], a[7]);
;         *(u32x4*)(O + (size_t)(row0 + ai * HALF + m * 16) * DFF + col0) = w; }
	v_pk_mul_f32 v[98:99], v[98:99], v[102:103] op_sel_hi:[1,0]
	v_pk_mul_f32 v[94:95], v[94:95], v[102:103] op_sel_hi:[1,0]
	v_mul_f32_e32 v104, 0xbfb8aa3b, v98
	v_pk_mul_f32 v[94:95], v[98:99], v[94:95]
	v_mul_f32_e32 v98, 0xbfb8aa3b, v99
	v_exp_f32_e32 v98, v98
	v_pk_mul_f32 v[96:97], v[96:97], v[102:103] op_sel_hi:[1,0]
	v_pk_mul_f32 v[90:91], v[90:91], v[102:103] op_sel_hi:[1,0]
	v_pk_mul_f32 v[86:87], v[86:87], v[102:103] op_sel_hi:[1,0]
	v_add_f32_e32 v98, 1.0, v98
	v_rcp_f32_e32 v105, v98
	v_pk_mul_f32 v[98:99], v[100:101], v[102:103] op_sel_hi:[1,0]
	v_pk_mul_f32 v[86:87], v[90:91], v[86:87]
	v_mul_f32_e32 v100, 0xbfb8aa3b, v98
	v_pk_mul_f32 v[96:97], v[98:99], v[96:97]
	v_mul_f32_e32 v98, 0xbfb8aa3b, v99
	v_exp_f32_e32 v98, v98
	v_pk_mul_f32 v[88:89], v[88:89], v[102:103] op_sel_hi:[1,0]
	v_exp_f32_e32 v104, v104
	v_exp_f32_e32 v100, v100
	v_add_f32_e32 v98, 1.0, v98
	v_rcp_f32_e32 v101, v98
	v_mul_f32_e32 v98, 0xbfb8aa3b, v90
	v_mul_f32_e32 v90, 0xbfb8aa3b, v91
	v_exp_f32_e32 v98, v98
	v_exp_f32_e32 v90, v90
	v_add_f32_e32 v104, 1.0, v104
	v_add_f32_e32 v100, 1.0, v100
	v_add_f32_e32 v98, 1.0, v98
	v_add_f32_e32 v90, 1.0, v90
	v_rcp_f32_e32 v98, v98
	v_rcp_f32_e32 v99, v90
	v_rcp_f32_e32 v104, v104
	v_rcp_f32_e32 v100, v100
	v_pk_mul_f32 v[90:91], v[86:87], v[98:99]
	v_pk_mul_f32 v[86:87], v[92:93], v[102:103] op_sel_hi:[1,0]
	v_pk_mul_f32 v[94:95], v[94:95], v[104:105]
	v_mul_f32_e32 v92, 0xbfb8aa3b, v86
	v_pk_mul_f32 v[88:89], v[86:87], v[88:89]
	v_mul_f32_e32 v86, 0xbfb8aa3b, v87
	v_exp_f32_e32 v92, v92
	v_exp_f32_e32 v86, v86
	v_pk_mul_f32 v[96:97], v[96:97], v[100:101]
	v_add_f32_e32 v92, 1.0, v92
	v_add_f32_e32 v86, 1.0, v86
	v_rcp_f32_e32 v92, v92
	v_rcp_f32_e32 v93, v86
	v_cvt_pk_bf16_f32 v86, v94, v95
	v_cvt_pk_bf16_f32 v87, v96, v97
	v_pk_mul_f32 v[92:93], v[88:89], v[92:93]
	v_cvt_pk_bf16_f32 v88, v90, v91
	v_or_b32_e32 v90, 32, v158
	v_mad_i64_i32 v[90:91], s[8:9], v90, s43, v[118:119]
	v_cvt_pk_bf16_f32 v89, v92, v93
	v_lshl_add_u64 v[90:91], v[90:91], 0, v[120:121]
	global_store_dwordx4 v[90:91], v[86:89], off
	s_nop 1
	v_mov_b32_e32 v86, v103
	v_pk_mul_f32 v[82:83], v[82:83], v[86:87] op_sel_hi:[1,0]
	s_nop 0
	v_mul_f32_e32 v87, 0xbfb8aa3b, v82
	v_exp_f32_e32 v87, v87
	s_nop 0
	v_add_f32_e32 v87, 1.0, v87
	v_pk_mul_f32 v[78:79], v[78:79], v[86:87] op_sel_hi:[1,0]
	v_pk_mul_f32 v[80:81], v[80:81], v[86:87] op_sel_hi:[1,0]
	v_pk_mul_f32 v[78:79], v[82:83], v[78:79]
	v_mul_f32_e32 v82, 0xbfb8aa3b, v83
	v_exp_f32_e32 v82, v82
	v_pk_mul_f32 v[74:75], v[74:75], v[86:87] op_sel_hi:[1,0]
	v_pk_mul_f32 v[70:71], v[70:71], v[86:87] op_sel_hi:[1,0]
	v_pk_mul_f32 v[72:73], v[72:73], v[86:87] op_sel_hi:[1,0]
	v_add_f32_e32 v82, 1.0, v82
	v_rcp_f32_e32 v89, v82
	v_pk_mul_f32 v[82:83], v[84:85], v[86:87] op_sel_hi:[1,0]
	v_pk_mul_f32 v[70:71], v[74:75], v[70:71]
	v_mul_f32_e32 v84, 0xbfb8aa3b, v82
	v_pk_mul_f32 v[80:81], v[82:83], v[80:81]
	v_mul_f32_e32 v82, 0xbfb8aa3b, v83
	v_exp_f32_e32 v82, v82
	v_exp_f32_e32 v84, v84
	v_rcp_f32_e32 v88, v87
	v_add_f32_e32 v82, 1.0, v82
	v_rcp_f32_e32 v85, v82
	v_mul_f32_e32 v82, 0xbfb8aa3b, v74
	v_mul_f32_e32 v74, 0xbfb8aa3b, v75
	v_exp_f32_e32 v82, v82
	v_exp_f32_e32 v74, v74
	v_add_f32_e32 v84, 1.0, v84
	v_rcp_f32_e32 v84, v84
	v_add_f32_e32 v82, 1.0, v82
	v_add_f32_e32 v74, 1.0, v74
	v_rcp_f32_e32 v82, v82
	v_rcp_f32_e32 v83, v74
	v_pk_mul_f32 v[78:79], v[78:79], v[88:89]
	v_pk_mul_f32 v[80:81], v[80:81], v[84:85]
	v_pk_mul_f32 v[74:75], v[70:71], v[82:83]
	v_pk_mul_f32 v[70:71], v[76:77], v[86:87] op_sel_hi:[1,0]
	s_nop 0
	v_mul_f32_e32 v76, 0xbfb8aa3b, v70
	v_pk_mul_f32 v[72:73], v[70:71], v[72:73]
	v_mul_f32_e32 v70, 0xbfb8aa3b, v71
	v_exp_f32_e32 v76, v76
	v_exp_f32_e32 v70, v70
	v_cvt_pk_bf16_f32 v71, v80, v81
	v_add_f32_e32 v76, 1.0, v76
	v_add_f32_e32 v70, 1.0, v70
	v_rcp_f32_e32 v76, v76
	v_rcp_f32_e32 v77, v70
	v_cvt_pk_bf16_f32 v70, v78, v79
	v_pk_mul_f32 v[76:77], v[72:73], v[76:77]
	v_cvt_pk_bf16_f32 v72, v74, v75
	v_or_b32_e32 v74, 48, v158
	v_mad_i64_i32 v[74:75], s[8:9], v74, s43, v[118:119]
	v_cvt_pk_bf16_f32 v73, v76, v77
	v_lshl_add_u64 v[74:75], v[74:75], 0, v[120:121]
	global_store_dwordx4 v[74:75], v[70:73], off
	ds_read2_b32 v[70:71], v159 offset0:128 offset1:144
	v_add_u32_e32 v74, 0x80, v158
	s_waitcnt lgkmcnt(0)
; DI unsigned pack2(float lo, float hi) { f32x2_t v = {lo, hi}; return __builtin_bit_cast(unsigned, __builtin_convertvector(v, bf16x2_t)); }
;   DI void operator()(const f32x4 (&acc)[2][2][4][2], const Unit& u, int wr, int wc, int fr, int fq, const PG8_LAS float* rt) const {
;     ...
;       for (int m = 0; m < 4; ++m) {
;         const float r = rt[ai * HALF + wr * 64 + m * 16 + fr];
;         float a[8];
; #pragma unroll
;         for (int n = 0; n < 2; ++n)
; #pragma unroll
;           for (int j = 0; j < 4; ++j) { const float u1 = acc[ai][0][m][n][j] * r, u3 = acc[ai][1][m][n][j] * r; a[4 * n + j] = u1 * u3 * __builtin_amdgcn_rcpf(1.f + __builtin_amdgcn_exp2f(-LOG2E * u1)); }
;         u32x4 w; w.x = pack2(a[0], a[1]); w.y = pack2(a[2], a[3]); w.z = pack2(a[4], a[5]); w.w = pack2(a[6], a[7]);
;         *(u32x4*)(O + (size_t)(row0 + ai * HALF + m * 16) * DFF + col0) = w; }
	v_pk_mul_f32 v[66:67], v[66:67], v[70:71] op_sel_hi:[1,0]
	v_pk_mul_f32 v[62:63], v[62:63], v[70:71] op_sel_hi:[1,0]
	v_mul_f32_e32 v72, 0xbfb8aa3b, v66
	v_pk_mul_f32 v[62:63], v[66:67], v[62:63]
	v_mul_f32_e32 v66, 0xbfb8aa3b, v67
	v_exp_f32_e32 v66, v66
	v_pk_mul_f32 v[64:65], v[64:65], v[70:71] op_sel_hi:[1,0]
	v_pk_mul_f32 v[58:59], v[58:59], v[70:71] op_sel_hi:[1,0]
	v_pk_mul_f32 v[54:55], v[54:55], v[70:71] op_sel_hi:[1,0]
	v_add_f32_e32 v66, 1.0, v66
	v_rcp_f32_e32 v73, v66
	v_pk_mul_f32 v[66:67], v[68:69], v[70:71] op_sel_hi:[1,0]
	v_pk_mul_f32 v[54:55], v[58:59], v[54:55]
	v_mul_f32_e32 v68, 0xbfb8aa3b, v66
	v_pk_mul_f32 v[64:65], v[66:67], v[64:65]
	v_mul_f32_e32 v66, 0xbfb8aa3b, v67
	v_exp_f32_e32 v66, v66
	v_pk_mul_f32 v[56:57], v[56:57], v[70:71] op_sel_hi:[1,0]
	v_exp_f32_e32 v72, v72
	v_exp_f32_e32 v68, v68
	v_add_f32_e32 v66, 1.0, v66
	v_rcp_f32_e32 v69, v66
	v_mul_f32_e32 v66, 0xbfb8aa3b, v58
	v_mul_f32_e32 v58, 0xbfb8aa3b, v59
	v_exp_f32_e32 v66, v66
	v_exp_f32_e32 v58, v58
	v_add_f32_e32 v72, 1.0, v72
	v_add_f32_e32 v68, 1.0, v68
	v_add_f32_e32 v66, 1.0, v66
	v_add_f32_e32 v58, 1.0, v58
	v_rcp_f32_e32 v66, v66
	v_rcp_f32_e32 v67, v58
	v_rcp_f32_e32 v72, v72
	v_rcp_f32_e32 v68, v68
	v_pk_mul_f32 v[58:59], v[54:55], v[66:67]
	v_pk_mul_f32 v[54:55], v[60:61], v[70:71] op_sel_hi:[1,0]
	v_pk_mul_f32 v[62:63], v[62:63], v[72:73]
	v_mul_f32_e32 v60, 0xbfb8aa3b, v54
	v_pk_mul_f32 v[56:57], v[54:55], v[56:57]
	v_mul_f32_e32 v54, 0xbfb8aa3b, v55
	v_exp_f32_e32 v60, v60
	v_exp_f32_e32 v54, v54
	v_pk_mul_f32 v[64:65], v[64:65], v[68:69]
	v_add_f32_e32 v60, 1.0, v60
	v_add_f32_e32 v54, 1.0, v54
	v_rcp_f32_e32 v60, v60
	v_rcp_f32_e32 v61, v54
	v_cvt_pk_bf16_f32 v54, v62, v63
	v_cvt_pk_bf16_f32 v55, v64, v65
	v_pk_mul_f32 v[60:61], v[56:57], v[60:61]
	v_cvt_pk_bf16_f32 v56, v58, v59
	v_mad_i64_i32 v[58:59], s[8:9], v74, s43, v[118:119]
	v_cvt_pk_bf16_f32 v57, v60, v61
	v_lshl_add_u64 v[58:59], v[58:59], 0, v[120:121]
	global_store_dwordx4 v[58:59], v[54:57], off
	s_nop 1
	v_mov_b32_e32 v54, v71
	v_pk_mul_f32 v[46:47], v[46:47], v[54:55] op_sel_hi:[1,0]
	s_nop 0
	v_mul_f32_e32 v55, 0xbfb8aa3b, v46
	v_exp_f32_e32 v55, v55
	s_nop 0
	v_add_f32_e32 v55, 1.0, v55
	v_pk_mul_f32 v[42:43], v[42:43], v[54:55] op_sel_hi:[1,0]
	v_pk_mul_f32 v[44:45], v[44:45], v[54:55] op_sel_hi:[1,0]
	v_pk_mul_f32 v[42:43], v[46:47], v[42:43]
	v_mul_f32_e32 v46, 0xbfb8aa3b, v47
	v_exp_f32_e32 v46, v46
	v_pk_mul_f32 v[38:39], v[38:39], v[54:55] op_sel_hi:[1,0]
	v_pk_mul_f32 v[34:35], v[34:35], v[54:55] op_sel_hi:[1,0]
	v_pk_mul_f32 v[36:37], v[36:37], v[54:55] op_sel_hi:[1,0]
	v_add_f32_e32 v46, 1.0, v46
	v_rcp_f32_e32 v57, v46
	v_pk_mul_f32 v[46:47], v[48:49], v[54:55] op_sel_hi:[1,0]
	v_pk_mul_f32 v[34:35], v[38:39], v[34:35]
	v_mul_f32_e32 v48, 0xbfb8aa3b, v46
	v_pk_mul_f32 v[44:45], v[46:47], v[44:45]
	v_mul_f32_e32 v46, 0xbfb8aa3b, v47
	v_exp_f32_e32 v46, v46
	v_exp_f32_e32 v48, v48
	v_rcp_f32_e32 v56, v55
	v_add_f32_e32 v46, 1.0, v46
	v_rcp_f32_e32 v49, v46
	v_mul_f32_e32 v46, 0xbfb8aa3b, v38
	v_mul_f32_e32 v38, 0xbfb8aa3b, v39
	v_exp_f32_e32 v46, v46
	v_exp_f32_e32 v38, v38
	v_add_f32_e32 v48, 1.0, v48
	v_rcp_f32_e32 v48, v48
	v_add_f32_e32 v46, 1.0, v46
	v_add_f32_e32 v38, 1.0, v38
	v_rcp_f32_e32 v46, v46
	v_rcp_f32_e32 v47, v38
	v_pk_mul_f32 v[42:43], v[42:43], v[56:57]
	v_pk_mul_f32 v[44:45], v[44:45], v[48:49]
	v_pk_mul_f32 v[38:39], v[34:35], v[46:47]
	v_pk_mul_f32 v[34:35], v[40:41], v[54:55] op_sel_hi:[1,0]
	s_nop 0
	v_mul_f32_e32 v40, 0xbfb8aa3b, v34
	v_pk_mul_f32 v[36:37], v[34:35], v[36:37]
	v_mul_f32_e32 v34, 0xbfb8aa3b, v35
	v_exp_f32_e32 v40, v40
	v_exp_f32_e32 v34, v34
	v_cvt_pk_bf16_f32 v35, v44, v45
	v_add_f32_e32 v40, 1.0, v40
	v_add_f32_e32 v34, 1.0, v34
	v_rcp_f32_e32 v40, v40
	v_rcp_f32_e32 v41, v34
	v_cvt_pk_bf16_f32 v34, v42, v43
	v_pk_mul_f32 v[40:41], v[36:37], v[40:41]
	v_cvt_pk_bf16_f32 v36, v38, v39
	v_add_u32_e32 v38, 0x90, v158
	v_mad_i64_i32 v[38:39], s[8:9], v38, s43, v[118:119]
	v_cvt_pk_bf16_f32 v37, v40, v41
	v_lshl_add_u64 v[38:39], v[38:39], 0, v[120:121]
	global_store_dwordx4 v[38:39], v[34:37], off
	ds_read2_b32 v[34:35], v159 offset0:160 offset1:176
	s_waitcnt lgkmcnt(0)
; DI unsigned pack2(float lo, float hi) { f32x2_t v = {lo, hi}; return __builtin_bit_cast(unsigned, __builtin_convertvector(v, bf16x2_t)); }
;   DI void operator()(const f32x4 (&acc)[2][2][4][2], const Unit& u, int wr, int wc, int fr, int fq, const PG8_LAS float* rt) const {
;     ...
;       for (int m = 0; m < 4; ++m) {
;         const float r = rt[ai * HALF + wr * 64 + m * 16 + fr];
;         float a[8];
; #pragma unroll
;         for (int n = 0; n < 2; ++n)
; #pragma unroll
;           for (int j = 0; j < 4; ++j) { const float u1 = acc[ai][0][m][n][j] * r, u3 = acc[ai][1][m][n][j] * r; a[4 * n + j] = u1 * u3 * __builtin_amdgcn_rcpf(1.f + __builtin_amdgcn_exp2f(-LOG2E * u1)); }
;         u32x4 w; w.x = pack2(a[0], a[1]); w.y = pack2(a[2], a[3]); w.z = pack2(a[4], a[5]); w.w = pack2(a[6], a[7]);
;         *(u32x4*)(O + (size_t)(row0 + ai * HALF + m * 16) * DFF + col0) = w; }
	v_pk_mul_f32 v[30:31], v[30:31], v[34:35] op_sel_hi:[1,0]
	v_pk_mul_f32 v[26:27], v[26:27], v[34:35] op_sel_hi:[1,0]
	v_mul_f32_e32 v36, 0xbfb8aa3b, v30
	v_pk_mul_f32 v[26:27], v[30:31], v[26:27]
	v_mul_f32_e32 v30, 0xbfb8aa3b, v31
	v_exp_f32_e32 v30, v30
	v_pk_mul_f32 v[28:29], v[28:29], v[34:35] op_sel_hi:[1,0]
	v_pk_mul_f32 v[22:23], v[22:23], v[34:35] op_sel_hi:[1,0]
	v_pk_mul_f32 v[18:19], v[18:19], v[34:35] op_sel_hi:[1,0]
	v_add_f32_e32 v30, 1.0, v30
	v_rcp_f32_e32 v37, v30
	v_pk_mul_f32 v[30:31], v[32:33], v[34:35] op_sel_hi:[1,0]
	v_pk_mul_f32 v[18:19], v[22:23], v[18:19]
	v_mul_f32_e32 v32, 0xbfb8aa3b, v30
	v_pk_mul_f32 v[28:29], v[30:31], v[28:29]
	v_mul_f32_e32 v30, 0xbfb8aa3b, v31
	v_exp_f32_e32 v30, v30
	v_pk_mul_f32 v[20:21], v[20:21], v[34:35] op_sel_hi:[1,0]
	v_exp_f32_e32 v36, v36
	v_exp_f32_e32 v32, v32
	v_add_f32_e32 v30, 1.0, v30
	v_rcp_f32_e32 v33, v30
	v_mul_f32_e32 v30, 0xbfb8aa3b, v22
	v_mul_f32_e32 v22, 0xbfb8aa3b, v23
	v_exp_f32_e32 v30, v30
	v_exp_f32_e32 v22, v22
	v_add_f32_e32 v36, 1.0, v36
	v_add_f32_e32 v32, 1.0, v32
	v_add_f32_e32 v30, 1.0, v30
	v_add_f32_e32 v22, 1.0, v22
	v_rcp_f32_e32 v30, v30
	v_rcp_f32_e32 v31, v22
	v_rcp_f32_e32 v36, v36
	v_rcp_f32_e32 v32, v32
	v_pk_mul_f32 v[22:23], v[18:19], v[30:31]
	v_pk_mul_f32 v[18:19], v[24:25], v[34:35] op_sel_hi:[1,0]
	v_pk_mul_f32 v[26:27], v[26:27], v[36:37]
	v_mul_f32_e32 v24, 0xbfb8aa3b, v18
	v_pk_mul_f32 v[20:21], v[18:19], v[20:21]
	v_mul_f32_e32 v18, 0xbfb8aa3b, v19
	v_exp_f32_e32 v24, v24
	v_exp_f32_e32 v18, v18
	v_pk_mul_f32 v[28:29], v[28:29], v[32:33]
	v_add_f32_e32 v24, 1.0, v24
	v_add_f32_e32 v18, 1.0, v18
	v_rcp_f32_e32 v24, v24
	v_rcp_f32_e32 v25, v18
	v_cvt_pk_bf16_f32 v18, v26, v27
	v_cvt_pk_bf16_f32 v19, v28, v29
	v_pk_mul_f32 v[24:25], v[20:21], v[24:25]
	v_cvt_pk_bf16_f32 v20, v22, v23
	v_add_u32_e32 v22, 0xa0, v158
	v_mad_i64_i32 v[22:23], s[8:9], v22, s43, v[118:119]
	v_cvt_pk_bf16_f32 v21, v24, v25
	v_lshl_add_u64 v[22:23], v[22:23], 0, v[120:121]
	global_store_dwordx4 v[22:23], v[18:21], off
	s_nop 1
	v_mov_b32_e32 v18, v35
	v_pk_mul_f32 v[14:15], v[14:15], v[18:19] op_sel_hi:[1,0]
	s_nop 0
	v_mul_f32_e32 v19, 0xbfb8aa3b, v14
	v_exp_f32_e32 v19, v19
	s_nop 0
	v_add_f32_e32 v19, 1.0, v19
	v_pk_mul_f32 v[10:11], v[10:11], v[18:19] op_sel_hi:[1,0]
	v_pk_mul_f32 v[12:13], v[12:13], v[18:19] op_sel_hi:[1,0]
	v_pk_mul_f32 v[10:11], v[14:15], v[10:11]
	v_mul_f32_e32 v14, 0xbfb8aa3b, v15
	v_exp_f32_e32 v14, v14
	v_pk_mul_f32 v[6:7], v[6:7], v[18:19] op_sel_hi:[1,0]
	v_pk_mul_f32 v[2:3], v[2:3], v[18:19] op_sel_hi:[1,0]
	v_pk_mul_f32 v[4:5], v[4:5], v[18:19] op_sel_hi:[1,0]
	v_add_f32_e32 v14, 1.0, v14
	v_rcp_f32_e32 v21, v14
	v_pk_mul_f32 v[14:15], v[16:17], v[18:19] op_sel_hi:[1,0]
	v_pk_mul_f32 v[2:3], v[6:7], v[2:3]
	v_mul_f32_e32 v16, 0xbfb8aa3b, v14
	v_pk_mul_f32 v[12:13], v[14:15], v[12:13]
	v_mul_f32_e32 v14, 0xbfb8aa3b, v15
	v_exp_f32_e32 v14, v14
	v_exp_f32_e32 v16, v16
	v_rcp_f32_e32 v20, v19
	v_add_f32_e32 v14, 1.0, v14
	v_rcp_f32_e32 v17, v14
	v_mul_f32_e32 v14, 0xbfb8aa3b, v6
	v_mul_f32_e32 v6, 0xbfb8aa3b, v7
	v_exp_f32_e32 v14, v14
	v_exp_f32_e32 v6, v6
	v_add_f32_e32 v16, 1.0, v16
	v_rcp_f32_e32 v16, v16
	v_add_f32_e32 v14, 1.0, v14
	v_add_f32_e32 v6, 1.0, v6
	v_rcp_f32_e32 v14, v14
	v_rcp_f32_e32 v15, v6
	v_pk_mul_f32 v[10:11], v[10:11], v[20:21]
	v_pk_mul_f32 v[12:13], v[12:13], v[16:17]
	v_pk_mul_f32 v[6:7], v[2:3], v[14:15]
	v_pk_mul_f32 v[2:3], v[8:9], v[18:19] op_sel_hi:[1,0]
	s_nop 0
	v_mul_f32_e32 v8, 0xbfb8aa3b, v2
	v_pk_mul_f32 v[4:5], v[2:3], v[4:5]
	v_mul_f32_e32 v2, 0xbfb8aa3b, v3
	v_exp_f32_e32 v8, v8
	v_exp_f32_e32 v2, v2
	v_cvt_pk_bf16_f32 v3, v12, v13
	v_add_f32_e32 v8, 1.0, v8
	v_add_f32_e32 v2, 1.0, v2
	v_rcp_f32_e32 v8, v8
	v_rcp_f32_e32 v9, v2
	v_cvt_pk_bf16_f32 v2, v10, v11
	v_pk_mul_f32 v[8:9], v[4:5], v[8:9]
	v_cvt_pk_bf16_f32 v4, v6, v7
	v_add_u32_e32 v6, 0xb0, v158
	v_mad_i64_i32 v[6:7], s[8:9], v6, s43, v[118:119]
	v_cvt_pk_bf16_f32 v5, v8, v9
	v_lshl_add_u64 v[6:7], v[6:7], 0, v[120:121]
	global_store_dwordx4 v[6:7], v[2:5], off
	s_cbranch_vccnz .LBB0_597
	s_waitcnt vmcnt(8)
	v_lshlrev_b32_e32 v2, 16, v50
	v_and_b32_e32 v3, 0xffff0000, v50
	v_add_f32_e32 v2, v2, v3
	v_lshlrev_b32_e32 v3, 16, v51
	v_add_f32_e32 v2, v2, v3
	v_and_b32_e32 v3, 0xffff0000, v51
	v_add_f32_e32 v2, v2, v3
	v_lshlrev_b32_e32 v3, 16, v52
	v_add_f32_e32 v2, v2, v3
	v_and_b32_e32 v3, 0xffff0000, v52
	v_add_f32_e32 v2, v2, v3
	v_lshlrev_b32_e32 v3, 16, v53
	v_add_f32_e32 v2, v2, v3
	v_and_b32_e32 v3, 0xffff0000, v53
	v_add_f32_e32 v2, v2, v3
	s_nop 1
	v_mov_b32_dpp v3, v2 quad_perm:[1,0,3,2] row_mask:0xf bank_mask:0xf
	s_and_saveexec_b64 s[8:9], s[36:37]
	s_xor_b64 s[28:29], exec, s[8:9]
	s_cbranch_execz .LBB0_596
	s_waitcnt lgkmcnt(0)
	v_add_f32_e32 v2, v2, v3
	v_fmamk_f32 v2, v2, 0x3a800000, v234
	v_cmp_gt_f32_e32 vcc, s97, v2
	v_mul_f32_e32 v3, 0x4b800000, v2
	s_lshl_b32 s8, s18, 10
	v_cndmask_b32_e32 v2, v2, v3, vcc
	v_rsq_f32_e32 v2, v2
	s_and_b32 s8, s8, 0x400
	v_mul_f32_e32 v3, 0x45800000, v2
	v_cndmask_b32_e32 v2, v2, v3, vcc
	v_add_u32_e32 v3, s8, v152
	ds_write_b32 v3, v2
	s_branch .LBB0_596
